# attention tile loop: next tile's K-fragment LDS address computed ahead of the mid-iteration barrier (own register)
# baseline (speedup 1.0000x reference)
.LBB0_429:
	v_exp_f32_e32 v199, v96
	v_exp_f32_e32 v221, v97
	v_exp_f32_e32 v226, v98
	v_exp_f32_e32 v227, v99
	v_exp_f32_e32 v228, v100
	v_exp_f32_e32 v229, v101
	v_exp_f32_e32 v230, v102
	v_exp_f32_e32 v231, v103
	v_exp_f32_e32 v232, v104
	v_exp_f32_e32 v233, v105
	v_exp_f32_e32 v234, v106
	v_exp_f32_e32 v235, v107
	v_exp_f32_e32 v236, v108
	v_exp_f32_e32 v237, v109
	v_exp_f32_e32 v238, v110
	v_exp_f32_e32 v239, v111
	v_add_u32_e32 v198, s17, v185
	s_waitcnt lgkmcnt(0)
	s_barrier
	ds_read_b128 v[202:205], v198 offset:49152
	ds_read_b128 v[206:209], v198 offset:57344
	v_xor_b32_e32 v64, 0x80000000, v195
	v_mov_b32_e32 v65, v64
	v_mov_b64_e32 v[66:67], v[64:65]
	v_mov_b64_e32 v[68:69], v[64:65]
	v_mov_b64_e32 v[70:71], v[64:65]
	v_mov_b64_e32 v[72:73], v[64:65]
	v_mov_b64_e32 v[74:75], v[64:65]
	v_mov_b64_e32 v[76:77], v[64:65]
	v_mov_b64_e32 v[78:79], v[64:65]
	v_add_u32_e32 v201, s17, v189
	v_exp_f32_e32 v80, v80
	s_waitcnt lgkmcnt(1)
	v_mfma_f32_32x32x16_bf16 v[96:111], v[202:205], v[124:127], v[64:79]
	v_exp_f32_e32 v81, v81
	v_exp_f32_e32 v82, v82
	v_exp_f32_e32 v83, v83
	v_exp_f32_e32 v84, v84
	v_exp_f32_e32 v85, v85
	v_exp_f32_e32 v86, v86
	v_exp_f32_e32 v87, v87
	s_waitcnt lgkmcnt(0)
	v_mfma_f32_32x32x16_bf16 v[64:79], v[206:209], v[124:127], v[64:79]
	ds_read_b128 v[202:205], v201 offset:49152
	ds_read_b128 v[206:209], v201 offset:57344
	v_add_u32_e32 v201, s17, v192
	v_exp_f32_e32 v240, v91
	v_exp_f32_e32 v241, v92
	v_cvt_pk_bf16_f32 v91, v230, v231
	v_cvt_pk_bf16_f32 v92, v232, v233
	s_waitcnt lgkmcnt(1)
	v_mfma_f32_32x32x16_bf16 v[96:111], v[202:205], v[120:123], v[96:111]
	ds_read_b128 v[202:205], v201 offset:49152
	ds_read_b128 v[210:213], v201 offset:57344
	v_add_u32_e32 v201, s17, v194
	s_waitcnt lgkmcnt(1)
	v_mfma_f32_32x32x16_bf16 v[96:111], v[202:205], v[116:119], v[96:111]
	v_exp_f32_e32 v203, v88
	v_add_f32_e32 v88, v221, v199
	v_add_f32_e32 v88, v226, v88
	v_add_f32_e32 v88, v227, v88
	v_add_f32_e32 v88, v228, v88
	v_add_f32_e32 v88, v229, v88
	v_add_f32_e32 v88, v230, v88
	v_add_f32_e32 v88, v231, v88
	v_add_f32_e32 v88, v232, v88
	v_add_f32_e32 v88, v233, v88
	v_mfma_f32_32x32x16_bf16 v[64:79], v[206:209], v[120:123], v[64:79]
	v_add_f32_e32 v88, v234, v88
	v_add_f32_e32 v88, v235, v88
	v_add_f32_e32 v88, v236, v88
	v_add_f32_e32 v88, v237, v88
	v_add_f32_e32 v88, v238, v88
	v_add_f32_e32 v88, v239, v88
	v_add_f32_e32 v88, v80, v88
	v_add_f32_e32 v88, v81, v88
	s_waitcnt lgkmcnt(0)
	v_mfma_f32_32x32x16_bf16 v[64:79], v[210:213], v[116:119], v[64:79]
	v_add_f32_e32 v88, v82, v88
	v_add_f32_e32 v88, v83, v88
	v_add_f32_e32 v88, v84, v88
	ds_read_b128 v[206:209], v201 offset:49152
	ds_read_b128 v[222:225], v201 offset:57344
	v_exp_f32_e32 v204, v89
	v_add_f32_e32 v88, v85, v88
	v_exp_f32_e32 v205, v90
	v_add_f32_e32 v88, v86, v88
	v_add_f32_e32 v88, v87, v88
	v_add_f32_e32 v88, v203, v88
	v_exp_f32_e32 v210, v93
	v_add_f32_e32 v88, v204, v88
	v_exp_f32_e32 v211, v94
	s_waitcnt lgkmcnt(1)
	v_mfma_f32_32x32x16_bf16 v[96:111], v[206:209], v[112:115], v[96:111]
	v_add_f32_e32 v88, v205, v88
	v_exp_f32_e32 v212, v95
	v_add_f32_e32 v88, v240, v88
	v_add_f32_e32 v88, v241, v88
	v_add_f32_e32 v88, v210, v88
	v_add_f32_e32 v88, v211, v88
	v_add_f32_e32 v201, v212, v88
	s_waitcnt lgkmcnt(0)
	v_mfma_f32_32x32x16_bf16 v[64:79], v[222:225], v[112:115], v[64:79]
	v_cvt_pk_bf16_f32 v88, v199, v221
	v_cvt_pk_bf16_f32 v89, v226, v227
	v_cvt_pk_bf16_f32 v90, v228, v229
	v_cvt_pk_bf16_f32 v93, v234, v235
	v_cvt_pk_bf16_f32 v94, v236, v237
	v_cvt_pk_bf16_f32 v95, v238, v239
	v_cvt_pk_bf16_f32 v80, v80, v81
	v_cvt_pk_bf16_f32 v81, v82, v83
	v_cvt_pk_bf16_f32 v82, v84, v85
	v_cvt_pk_bf16_f32 v83, v86, v87
	v_cvt_pk_bf16_f32 v84, v203, v204
	v_cvt_pk_bf16_f32 v85, v205, v240
	v_cvt_pk_bf16_f32 v86, v241, v210
	v_cvt_pk_bf16_f32 v87, v211, v212
	s_cmpk_gt_u32 s6, 0x7c
	s_cselect_b64 s[4:5], -1, 0
	s_and_b64 vcc, exec, s[4:5]
	s_cbranch_vccnz .Lattn_a0_lastw
	global_load_dwordx4 v[132:135], v244, s[98:99]
	global_load_dwordx4 v[128:131], v242, s[98:99]
	global_load_dwordx4 v[140:143], v245, s[98:99]
	global_load_dwordx4 v[136:139], v243, s[98:99]
	s_add_u32 s98, s98, 0x10000
	s_addc_u32 s99, s99, 0
